# v18 + nt hint on the y_b epilogue's last-use loads (y_a tile and gates)
# baseline (speedup 1.0000x reference)
; __device__ __forceinline__ unsigned cvtpk(float lo, float hi) { f32x2_t v = {lo, hi}; f16x2_t b = __builtin_convertvector(v, f16x2_t); return __builtin_bit_cast(unsigned, b); }
; __device__ __forceinline__ float bflo(unsigned w) { const f16x2_t b = __builtin_bit_cast(f16x2_t, w); return (float)b[0]; }
; __device__ __forceinline__ float bfhi(unsigned w) { const f16x2_t b = __builtin_bit_cast(f16x2_t, w); return (float)b[1]; }
;     __device__ __forceinline__ void operator()(const f32x4 (&acc)[2][2][4][2], const Unit& u, int wr, int wc, int fr, int fq) const {
;         const int row0 = u.pm * BM + wr * 64 + fr, col0 = u.pn * BM + wc * 32 + 8 * fq;
; #pragma unroll
;         for (int ai = 0; ai < 2; ++ai)
; #pragma unroll
;             for (int mh = 0; mh < 2; ++mh) { u32x4 gv[2][2]; u32x4 sv[2][2];
; #pragma unroll
;                 for (int mm = 0; mm < 2; ++mm)
; #pragma unroll
;                     for (int bj = 0; bj < 2; ++bj) { const int row = row0 + ai * HALF + (2 * mh + mm) * 16, col = col0 + bj * HALF;
;                         gv[mm][bj] = *(const u32x4*)(G + (size_t)row * 2048 + 1024 + col); sv[mm][bj] = *(const u32x4*)(scr + (size_t)row * 1024 + col); }
; #pragma unroll
;                 for (int mm = 0; mm < 2; ++mm)
; #pragma unroll
;                     for (int bj = 0; bj < 2; ++bj) { const int m = 2 * mh + mm; const int row = row0 + ai * HALF + m * 16, col = col0 + bj * HALF; const u32x4 g = gv[mm][bj]; const u32x4 sw = sv[mm][bj]; const f32x4 s0 = (f32x4){bflo(sw.x), bfhi(sw.x), bflo(sw.y), bfhi(sw.y)}, s1 = (f32x4){bflo(sw.z), bfhi(sw.z), bflo(sw.w), bfhi(sw.w)};
;                         f32x4 v0 = acc[ai][bj][m][0], v1 = acc[ai][bj][m][1];
;                         v0[0] = s0[0] + v0[0] * sigmoidf_(bflo(g.x)); v0[1] = s0[1] + v0[1] * sigmoidf_(bfhi(g.x)); v0[2] = s0[2] + v0[2] * sigmoidf_(bflo(g.y)); v0[3] = s0[3] + v0[3] * sigmoidf_(bfhi(g.y));
;                         v1[0] = s1[0] + v1[0] * sigmoidf_(bflo(g.z)); v1[1] = s1[1] + v1[1] * sigmoidf_(bfhi(g.z)); v1[2] = s1[2] + v1[2] * sigmoidf_(bflo(g.w)); v1[3] = s1[3] + v1[3] * sigmoidf_(bfhi(g.w));
;                         u32x4 w; w.x = cvtpk(v0[0], v0[1]); w.y = cvtpk(v0[2], v0[3]); w.z = cvtpk(v1[0], v1[1]); w.w = cvtpk(v1[2], v1[3]);
;                         *(u32x4*)(mrg + (size_t)row * 1024 + col) = w; }
.LBB0_756:
	v_lshl_add_u32 v154, s24, 8, v178
	v_lshl_or_b32 v114, s5, 8, v180
	v_ashrrev_i32_e32 v155, 31, v154
	v_ashrrev_i32_e32 v115, 31, v114
	v_lshlrev_b64 v[172:173], 11, v[154:155]
	v_lshl_add_u64 v[118:119], s[74:75], 0, v[172:173]
	v_lshlrev_b64 v[152:153], 1, v[114:115]
	v_lshl_add_u64 v[114:115], v[118:119], 0, v[152:153]
	global_load_dwordx4 v[182:185], v[114:115], off nt
	global_load_dwordx4 v[138:141], v[114:115], off offset:256 nt
	v_or_b32_e32 v114, 16, v154
	v_lshlrev_b64 v[116:117], 12, v[154:155]
	s_mov_b64 s[14:15], s[66:67]
	v_ashrrev_i32_e32 v115, 31, v114
	v_lshl_add_u64 v[116:117], s[14:15], 0, v[116:117]
	v_lshlrev_b64 v[156:157], 11, v[114:115]
	v_lshl_add_u64 v[160:161], v[116:117], 0, v[152:153]
	v_lshlrev_b64 v[116:117], 12, v[114:115]
	v_lshl_add_u64 v[114:115], s[74:75], 0, v[156:157]
	v_lshl_add_u64 v[116:117], s[14:15], 0, v[116:117]
	v_lshl_add_u64 v[114:115], v[114:115], 0, v[152:153]
	v_lshl_add_u64 v[158:159], v[116:117], 0, v[152:153]
	global_load_dwordx4 v[118:121], v[114:115], off nt
	s_nop 0
	global_load_dwordx4 v[114:117], v[114:115], off offset:256 nt
	s_nop 0
	global_load_dwordx4 v[188:191], v[160:161], off offset:2048 nt
	v_readlane_b32 s24, v253, 13
	v_readlane_b32 s25, v253, 14
	v_readlane_b32 s76, v253, 5
	s_andn2_b64 vcc, exec, s[38:39]
	v_readlane_b32 s77, v253, 6
	v_readlane_b32 s78, v253, 7
	v_readlane_b32 s79, v253, 8
	s_mov_b32 s37, 0x10000
	s_mov_b32 s30, 0x8000
	s_mov_b32 s31, s65
	s_waitcnt vmcnt(0)
	v_cvt_f32_f16_e32 v194, v182
	v_cvt_f32_f16_sdwa v195, v182 dst_sel:DWORD dst_unused:UNUSED_PAD src0_sel:WORD_1
	v_cvt_f32_f16_e32 v182, v183
	v_cvt_f32_f16_sdwa v183, v183 dst_sel:DWORD dst_unused:UNUSED_PAD src0_sel:WORD_1
	v_cvt_f32_f16_e32 v155, v188
	v_mul_f32_e32 v155, 0xbfb8aa3b, v155
	v_exp_f32_e32 v155, v155
	s_nop 0
	v_add_f32_e32 v155, 1.0, v155
	v_rcp_f32_e32 v192, v155
	v_cvt_f32_f16_sdwa v155, v188 dst_sel:DWORD dst_unused:UNUSED_PAD src0_sel:WORD_1
	v_mul_f32_e32 v155, 0xbfb8aa3b, v155
	v_exp_f32_e32 v155, v155
	s_nop 0
	v_add_f32_e32 v155, 1.0, v155
	v_rcp_f32_e32 v193, v155
	v_cvt_f32_f16_e32 v155, v189
	v_pk_fma_f32 v[134:135], v[134:135], v[192:193], v[194:195]
	v_mul_f32_e32 v155, 0xbfb8aa3b, v155
	v_exp_f32_e32 v155, v155
	s_nop 0
	v_add_f32_e32 v155, 1.0, v155
	v_rcp_f32_e32 v188, v155
	v_cvt_f32_f16_sdwa v155, v189 dst_sel:DWORD dst_unused:UNUSED_PAD src0_sel:WORD_1
	v_mul_f32_e32 v155, 0xbfb8aa3b, v155
	v_exp_f32_e32 v155, v155
	s_nop 0
	v_add_f32_e32 v155, 1.0, v155
	v_rcp_f32_e32 v189, v155
	v_cvt_f32_f16_e32 v155, v190
	v_pk_fma_f32 v[136:137], v[136:137], v[188:189], v[182:183]
	v_mul_f32_e32 v155, 0xbfb8aa3b, v155
	v_exp_f32_e32 v155, v155
	v_cvt_f32_f16_e32 v188, v184
	v_cvt_f32_f16_sdwa v189, v184 dst_sel:DWORD dst_unused:UNUSED_PAD src0_sel:WORD_1
	v_cvt_f32_f16_e32 v184, v185
	v_add_f32_e32 v155, 1.0, v155
	v_rcp_f32_e32 v182, v155
	v_cvt_f32_f16_sdwa v155, v190 dst_sel:DWORD dst_unused:UNUSED_PAD src0_sel:WORD_1
	v_cvt_f32_f16_sdwa v185, v185 dst_sel:DWORD dst_unused:UNUSED_PAD src0_sel:WORD_1
	v_mul_f32_e32 v155, 0xbfb8aa3b, v155
	v_exp_f32_e32 v155, v155
	s_nop 0
	v_add_f32_e32 v155, 1.0, v155
	v_rcp_f32_e32 v183, v155
	v_cvt_f32_f16_e32 v155, v191
	v_pk_fma_f32 v[122:123], v[122:123], v[182:183], v[188:189]
	v_mul_f32_e32 v155, 0xbfb8aa3b, v155
	v_exp_f32_e32 v155, v155
	s_nop 0
	v_add_f32_e32 v155, 1.0, v155
	v_rcp_f32_e32 v182, v155
	v_cvt_f32_f16_sdwa v155, v191 dst_sel:DWORD dst_unused:UNUSED_PAD src0_sel:WORD_1
	v_mul_f32_e32 v155, 0xbfb8aa3b, v155
	v_exp_f32_e32 v155, v155
	s_nop 0
	v_add_f32_e32 v155, 1.0, v155
	v_rcp_f32_e32 v183, v155
	s_nop 0
	v_pk_fma_f32 v[124:125], v[124:125], v[182:183], v[184:185]
	v_cvt_pk_f16_f32 v184, v122, v123
	v_lshl_add_u64 v[122:123], s[24:25], 0, v[172:173]
	v_cvt_pk_f16_f32 v182, v134, v135
	v_cvt_pk_f16_f32 v183, v136, v137
	v_cvt_pk_f16_f32 v185, v124, v125
	v_lshl_add_u64 v[134:135], v[122:123], 0, v[152:153]
	global_load_dwordx4 v[122:125], v[158:159], off offset:2048 nt
	s_nop 0
	global_store_dwordx4 v[134:135], v[182:185], off
	global_load_dwordx4 v[182:185], v[160:161], off offset:2304 nt
	v_cvt_f32_f16_e32 v160, v138
	v_cvt_f32_f16_sdwa v161, v138 dst_sel:DWORD dst_unused:UNUSED_PAD src0_sel:WORD_1
	v_cvt_f32_f16_e32 v138, v139
	v_cvt_f32_f16_sdwa v139, v139 dst_sel:DWORD dst_unused:UNUSED_PAD src0_sel:WORD_1
	s_waitcnt vmcnt(0)
; __device__ __forceinline__ unsigned cvtpk(float lo, float hi) { f32x2_t v = {lo, hi}; f16x2_t b = __builtin_convertvector(v, f16x2_t); return __builtin_bit_cast(unsigned, b); }
; __device__ __forceinline__ float bflo(unsigned w) { const f16x2_t b = __builtin_bit_cast(f16x2_t, w); return (float)b[0]; }
; __device__ __forceinline__ float bfhi(unsigned w) { const f16x2_t b = __builtin_bit_cast(f16x2_t, w); return (float)b[1]; }
; __device__ __forceinline__ float sigmoidf_(float x) { return __builtin_amdgcn_rcpf(1.0f + __builtin_amdgcn_exp2f(-1.4426950408889634f * x)); }
;     __device__ __forceinline__ void operator()(const f32x4 (&acc)[2][2][4][2], const Unit& u, int wr, int wc, int fr, int fq) const {
;     ...
;                     for (int bj = 0; bj < 2; ++bj) { const int row = row0 + ai * HALF + (2 * mh + mm) * 16, col = col0 + bj * HALF;
;                         gv[mm][bj] = *(const u32x4*)(G + (size_t)row * 2048 + 1024 + col); sv[mm][bj] = *(const u32x4*)(scr + (size_t)row * 1024 + col); }
; #pragma unroll
;                 for (int mm = 0; mm < 2; ++mm)
; #pragma unroll
;                     for (int bj = 0; bj < 2; ++bj) { const int m = 2 * mh + mm; const int row = row0 + ai * HALF + m * 16, col = col0 + bj * HALF; const u32x4 g = gv[mm][bj]; const u32x4 sw = sv[mm][bj]; const f32x4 s0 = (f32x4){bflo(sw.x), bfhi(sw.x), bflo(sw.y), bfhi(sw.y)}, s1 = (f32x4){bflo(sw.z), bfhi(sw.z), bflo(sw.w), bfhi(sw.w)};
;                         f32x4 v0 = acc[ai][bj][m][0], v1 = acc[ai][bj][m][1];
;                         v0[0] = s0[0] + v0[0] * sigmoidf_(bflo(g.x)); v0[1] = s0[1] + v0[1] * sigmoidf_(bfhi(g.x)); v0[2] = s0[2] + v0[2] * sigmoidf_(bflo(g.y)); v0[3] = s0[3] + v0[3] * sigmoidf_(bfhi(g.y));
;                         v1[0] = s1[0] + v1[0] * sigmoidf_(bflo(g.z)); v1[1] = s1[1] + v1[1] * sigmoidf_(bfhi(g.z)); v1[2] = s1[2] + v1[2] * sigmoidf_(bflo(g.w)); v1[3] = s1[3] + v1[3] * sigmoidf_(bfhi(g.w));
;                         u32x4 w; w.x = cvtpk(v0[0], v0[1]); w.y = cvtpk(v0[2], v0[3]); w.z = cvtpk(v1[0], v1[1]); w.w = cvtpk(v1[2], v1[3]);
;                         *(u32x4*)(mrg + (size_t)row * 1024 + col) = w; }
	v_cvt_f32_f16_e32 v136, v182
	v_cvt_f32_f16_sdwa v137, v182 dst_sel:DWORD dst_unused:UNUSED_PAD src0_sel:WORD_1
	v_mul_f32_e32 v136, 0xbfb8aa3b, v136
	v_mul_f32_e32 v137, 0xbfb8aa3b, v137
	v_exp_f32_e32 v136, v136
	v_exp_f32_e32 v137, v137
	v_add_f32_e32 v136, 1.0, v136
	v_add_f32_e32 v137, 1.0, v137
	v_rcp_f32_e32 v136, v136
	v_rcp_f32_e32 v137, v137
	s_nop 0
	v_pk_fma_f32 v[130:131], v[130:131], v[136:137], v[160:161]
	v_cvt_f32_f16_e32 v136, v183
	v_cvt_f32_f16_sdwa v137, v183 dst_sel:DWORD dst_unused:UNUSED_PAD src0_sel:WORD_1
	v_cvt_pk_f16_f32 v130, v130, v131
	v_mul_f32_e32 v136, 0xbfb8aa3b, v136
	v_mul_f32_e32 v137, 0xbfb8aa3b, v137
	v_exp_f32_e32 v136, v136
	v_exp_f32_e32 v137, v137
	v_add_f32_e32 v136, 1.0, v136
	v_add_f32_e32 v137, 1.0, v137
	v_rcp_f32_e32 v136, v136
	v_rcp_f32_e32 v137, v137
	s_nop 0
	v_pk_fma_f32 v[132:133], v[132:133], v[136:137], v[138:139]
	v_cvt_f32_f16_e32 v136, v184
	v_cvt_f32_f16_sdwa v137, v184 dst_sel:DWORD dst_unused:UNUSED_PAD src0_sel:WORD_1
	v_cvt_f32_f16_e32 v138, v140
	v_cvt_f32_f16_sdwa v139, v140 dst_sel:DWORD dst_unused:UNUSED_PAD src0_sel:WORD_1
	v_mul_f32_e32 v136, 0xbfb8aa3b, v136
	v_mul_f32_e32 v137, 0xbfb8aa3b, v137
	v_exp_f32_e32 v136, v136
	v_exp_f32_e32 v137, v137
	v_cvt_pk_f16_f32 v131, v132, v133
	v_add_f32_e32 v136, 1.0, v136
	v_add_f32_e32 v137, 1.0, v137
	v_rcp_f32_e32 v136, v136
	v_rcp_f32_e32 v137, v137
	s_nop 0
	v_pk_fma_f32 v[126:127], v[126:127], v[136:137], v[138:139]
	v_cvt_f32_f16_e32 v136, v185
	v_cvt_f32_f16_sdwa v137, v185 dst_sel:DWORD dst_unused:UNUSED_PAD src0_sel:WORD_1
	v_cvt_f32_f16_e32 v138, v141
	v_cvt_f32_f16_sdwa v139, v141 dst_sel:DWORD dst_unused:UNUSED_PAD src0_sel:WORD_1
	v_mul_f32_e32 v136, 0xbfb8aa3b, v136
	v_mul_f32_e32 v137, 0xbfb8aa3b, v137
	v_exp_f32_e32 v136, v136
	v_exp_f32_e32 v137, v137
	v_cvt_pk_f16_f32 v132, v126, v127
	v_add_f32_e32 v136, 1.0, v136
	v_add_f32_e32 v137, 1.0, v137
	v_rcp_f32_e32 v136, v136
	v_rcp_f32_e32 v137, v137
	s_nop 0
	v_pk_fma_f32 v[128:129], v[128:129], v[136:137], v[138:139]
	s_nop 0
	v_cvt_pk_f16_f32 v133, v128, v129
	global_load_dwordx4 v[126:129], v[158:159], off offset:2304 nt
	s_nop 0
	global_store_dwordx4 v[134:135], v[130:133], off offset:256
	s_nop 1
	v_cvt_f32_f16_e32 v130, v122
	v_cvt_f32_f16_sdwa v122, v122 dst_sel:DWORD dst_unused:UNUSED_PAD src0_sel:WORD_1
	v_cvt_f32_f16_e32 v132, v118
	v_cvt_f32_f16_sdwa v133, v118 dst_sel:DWORD dst_unused:UNUSED_PAD src0_sel:WORD_1
	v_cvt_f32_f16_e32 v118, v123
	v_mul_f32_e32 v122, 0xbfb8aa3b, v122
	v_exp_f32_e32 v122, v122
	v_mul_f32_e32 v130, 0xbfb8aa3b, v130
	v_mul_f32_e32 v118, 0xbfb8aa3b, v118
	v_exp_f32_e32 v118, v118
	v_add_f32_e32 v122, 1.0, v122
	v_rcp_f32_e32 v131, v122
	v_exp_f32_e32 v130, v130
	v_add_f32_e32 v118, 1.0, v118
	v_rcp_f32_e32 v122, v118
	v_cvt_f32_f16_sdwa v118, v123 dst_sel:DWORD dst_unused:UNUSED_PAD src0_sel:WORD_1
	v_add_f32_e32 v130, 1.0, v130
	v_rcp_f32_e32 v130, v130
	v_mul_f32_e32 v118, 0xbfb8aa3b, v118
	v_exp_f32_e32 v118, v118
	v_pk_fma_f32 v[110:111], v[110:111], v[130:131], v[132:133]
	v_add_f32_e32 v118, 1.0, v118
	v_rcp_f32_e32 v123, v118
	v_cvt_f32_f16_e32 v118, v119
	v_cvt_f32_f16_sdwa v119, v119 dst_sel:DWORD dst_unused:UNUSED_PAD src0_sel:WORD_1
	v_pk_fma_f32 v[112:113], v[112:113], v[122:123], v[118:119]
	v_cvt_f32_f16_e32 v118, v124
	v_cvt_f32_f16_sdwa v119, v124 dst_sel:DWORD dst_unused:UNUSED_PAD src0_sel:WORD_1
	v_cvt_f32_f16_e32 v122, v120
	v_cvt_f32_f16_sdwa v123, v120 dst_sel:DWORD dst_unused:UNUSED_PAD src0_sel:WORD_1
	v_mul_f32_e32 v118, 0xbfb8aa3b, v118
	v_mul_f32_e32 v119, 0xbfb8aa3b, v119
	v_exp_f32_e32 v118, v118
	v_exp_f32_e32 v119, v119
	v_cvt_f32_f16_e32 v120, v121
	v_cvt_f32_f16_sdwa v121, v121 dst_sel:DWORD dst_unused:UNUSED_PAD src0_sel:WORD_1
	v_add_f32_e32 v118, 1.0, v118
	v_add_f32_e32 v119, 1.0, v119
	v_rcp_f32_e32 v118, v118
	v_rcp_f32_e32 v119, v119
	s_nop 0
	v_pk_fma_f32 v[106:107], v[106:107], v[118:119], v[122:123]
	v_cvt_f32_f16_e32 v118, v125
	v_cvt_f32_f16_sdwa v119, v125 dst_sel:DWORD dst_unused:UNUSED_PAD src0_sel:WORD_1
	v_mul_f32_e32 v118, 0xbfb8aa3b, v118
	v_mul_f32_e32 v119, 0xbfb8aa3b, v119
	v_exp_f32_e32 v118, v118
	v_exp_f32_e32 v119, v119
	v_add_f32_e32 v118, 1.0, v118
	v_add_f32_e32 v119, 1.0, v119
	v_rcp_f32_e32 v118, v118
	v_rcp_f32_e32 v119, v119
	s_nop 0
	v_pk_fma_f32 v[118:119], v[108:109], v[118:119], v[120:121]
	v_cvt_pk_f16_f32 v108, v110, v111
	v_cvt_pk_f16_f32 v110, v106, v107
	v_lshl_add_u64 v[106:107], s[24:25], 0, v[156:157]
	v_cvt_pk_f16_f32 v109, v112, v113
	v_cvt_pk_f16_f32 v111, v118, v119
	v_lshl_add_u64 v[106:107], v[106:107], 0, v[152:153]
	global_store_dwordx4 v[106:107], v[108:111], off
	s_waitcnt vmcnt(2)
; __device__ __forceinline__ unsigned cvtpk(float lo, float hi) { f32x2_t v = {lo, hi}; f16x2_t b = __builtin_convertvector(v, f16x2_t); return __builtin_bit_cast(unsigned, b); }
; __device__ __forceinline__ float bflo(unsigned w) { const f16x2_t b = __builtin_bit_cast(f16x2_t, w); return (float)b[0]; }
; __device__ __forceinline__ float bfhi(unsigned w) { const f16x2_t b = __builtin_bit_cast(f16x2_t, w); return (float)b[1]; }
; __device__ __forceinline__ float sigmoidf_(float x) { return __builtin_amdgcn_rcpf(1.0f + __builtin_amdgcn_exp2f(-1.4426950408889634f * x)); }
;     __device__ __forceinline__ void operator()(const f32x4 (&acc)[2][2][4][2], const Unit& u, int wr, int wc, int fr, int fq) const {
;     ...
;             for (int mh = 0; mh < 2; ++mh) { u32x4 gv[2][2]; u32x4 sv[2][2];
; #pragma unroll
;                 for (int mm = 0; mm < 2; ++mm)
; #pragma unroll
;                     for (int bj = 0; bj < 2; ++bj) { const int row = row0 + ai * HALF + (2 * mh + mm) * 16, col = col0 + bj * HALF;
;                         gv[mm][bj] = *(const u32x4*)(G + (size_t)row * 2048 + 1024 + col); sv[mm][bj] = *(const u32x4*)(scr + (size_t)row * 1024 + col); }
; #pragma unroll
;                 for (int mm = 0; mm < 2; ++mm)
; #pragma unroll
;                     for (int bj = 0; bj < 2; ++bj) { const int m = 2 * mh + mm; const int row = row0 + ai * HALF + m * 16, col = col0 + bj * HALF; const u32x4 g = gv[mm][bj]; const u32x4 sw = sv[mm][bj]; const f32x4 s0 = (f32x4){bflo(sw.x), bfhi(sw.x), bflo(sw.y), bfhi(sw.y)}, s1 = (f32x4){bflo(sw.z), bfhi(sw.z), bflo(sw.w), bfhi(sw.w)};
;                         f32x4 v0 = acc[ai][bj][m][0], v1 = acc[ai][bj][m][1];
;                         v0[0] = s0[0] + v0[0] * sigmoidf_(bflo(g.x)); v0[1] = s0[1] + v0[1] * sigmoidf_(bfhi(g.x)); v0[2] = s0[2] + v0[2] * sigmoidf_(bflo(g.y)); v0[3] = s0[3] + v0[3] * sigmoidf_(bfhi(g.y));
;                         v1[0] = s1[0] + v1[0] * sigmoidf_(bflo(g.z)); v1[1] = s1[1] + v1[1] * sigmoidf_(bfhi(g.z)); v1[2] = s1[2] + v1[2] * sigmoidf_(bflo(g.w)); v1[3] = s1[3] + v1[3] * sigmoidf_(bfhi(g.w));
;                         u32x4 w; w.x = cvtpk(v0[0], v0[1]); w.y = cvtpk(v0[2], v0[3]); w.z = cvtpk(v1[0], v1[1]); w.w = cvtpk(v1[2], v1[3]);
;                         *(u32x4*)(mrg + (size_t)row * 1024 + col) = w; }
	s_nop 0
	v_cvt_f32_f16_e32 v108, v126
	v_cvt_f32_f16_sdwa v109, v126 dst_sel:DWORD dst_unused:UNUSED_PAD src0_sel:WORD_1
	v_cvt_f32_f16_e32 v110, v114
	v_cvt_f32_f16_sdwa v111, v114 dst_sel:DWORD dst_unused:UNUSED_PAD src0_sel:WORD_1
	v_mul_f32_e32 v108, 0xbfb8aa3b, v108
	v_mul_f32_e32 v109, 0xbfb8aa3b, v109
	v_exp_f32_e32 v108, v108
	v_exp_f32_e32 v109, v109
	v_add_f32_e32 v108, 1.0, v108
	v_add_f32_e32 v109, 1.0, v109
	v_rcp_f32_e32 v108, v108
	v_rcp_f32_e32 v109, v109
	s_nop 0
	v_pk_fma_f32 v[102:103], v[102:103], v[108:109], v[110:111]
	v_cvt_f32_f16_e32 v108, v127
	v_cvt_f32_f16_sdwa v109, v127 dst_sel:DWORD dst_unused:UNUSED_PAD src0_sel:WORD_1
	v_cvt_f32_f16_e32 v110, v115
	v_cvt_f32_f16_sdwa v111, v115 dst_sel:DWORD dst_unused:UNUSED_PAD src0_sel:WORD_1
	v_mul_f32_e32 v108, 0xbfb8aa3b, v108
	v_mul_f32_e32 v109, 0xbfb8aa3b, v109
	v_exp_f32_e32 v108, v108
	v_exp_f32_e32 v109, v109
	v_add_f32_e32 v108, 1.0, v108
	v_add_f32_e32 v109, 1.0, v109
	v_rcp_f32_e32 v108, v108
	v_rcp_f32_e32 v109, v109
	s_nop 0
	v_pk_fma_f32 v[104:105], v[104:105], v[108:109], v[110:111]
	v_cvt_f32_f16_e32 v108, v128
	v_cvt_f32_f16_sdwa v109, v128 dst_sel:DWORD dst_unused:UNUSED_PAD src0_sel:WORD_1
	v_cvt_f32_f16_e32 v110, v116
	v_cvt_f32_f16_sdwa v111, v116 dst_sel:DWORD dst_unused:UNUSED_PAD src0_sel:WORD_1
	v_mul_f32_e32 v108, 0xbfb8aa3b, v108
	v_mul_f32_e32 v109, 0xbfb8aa3b, v109
	v_exp_f32_e32 v108, v108
	v_exp_f32_e32 v109, v109
	v_add_f32_e32 v108, 1.0, v108
	v_add_f32_e32 v109, 1.0, v109
	v_rcp_f32_e32 v108, v108
	v_rcp_f32_e32 v109, v109
	s_nop 0
	v_pk_fma_f32 v[108:109], v[98:99], v[108:109], v[110:111]
	v_cvt_f32_f16_e32 v98, v129
	v_cvt_f32_f16_sdwa v99, v129 dst_sel:DWORD dst_unused:UNUSED_PAD src0_sel:WORD_1
	v_cvt_f32_f16_e32 v110, v117
	v_cvt_f32_f16_sdwa v111, v117 dst_sel:DWORD dst_unused:UNUSED_PAD src0_sel:WORD_1
	v_mul_f32_e32 v98, 0xbfb8aa3b, v98
	v_mul_f32_e32 v99, 0xbfb8aa3b, v99
	v_exp_f32_e32 v98, v98
	v_exp_f32_e32 v99, v99
	v_add_f32_e32 v98, 1.0, v98
	v_add_f32_e32 v99, 1.0, v99
	v_rcp_f32_e32 v98, v98
	v_rcp_f32_e32 v99, v99
	s_nop 0
	v_pk_fma_f32 v[110:111], v[100:101], v[98:99], v[110:111]
	v_cvt_pk_f16_f32 v98, v102, v103
	v_cvt_pk_f16_f32 v99, v104, v105
	v_cvt_pk_f16_f32 v100, v108, v109
	v_cvt_pk_f16_f32 v101, v110, v111
	global_store_dwordx4 v[106:107], v[98:101], off offset:256
	s_nop 1
	v_or_b32_e32 v98, 32, v154
	v_ashrrev_i32_e32 v99, 31, v98
	v_lshlrev_b64 v[114:115], 11, v[98:99]
	v_lshlrev_b64 v[100:101], 12, v[98:99]
	v_lshl_add_u64 v[98:99], s[74:75], 0, v[114:115]
	v_lshl_add_u64 v[98:99], v[98:99], 0, v[152:153]
	global_load_dwordx4 v[118:121], v[98:99], off nt
	global_load_dwordx4 v[106:109], v[98:99], off offset:256 nt
	v_or_b32_e32 v98, 48, v154
	v_ashrrev_i32_e32 v99, 31, v98
	v_lshl_add_u64 v[100:101], s[14:15], 0, v[100:101]
	v_lshlrev_b64 v[110:111], 11, v[98:99]
	v_lshl_add_u64 v[116:117], v[100:101], 0, v[152:153]
	v_lshlrev_b64 v[100:101], 12, v[98:99]
	v_lshl_add_u64 v[98:99], s[74:75], 0, v[110:111]
	v_lshl_add_u64 v[100:101], s[14:15], 0, v[100:101]
	v_lshl_add_u64 v[98:99], v[98:99], 0, v[152:153]
	v_lshl_add_u64 v[112:113], v[100:101], 0, v[152:153]
	global_load_dwordx4 v[102:105], v[98:99], off nt
	s_nop 0
	global_load_dwordx4 v[98:101], v[98:99], off offset:256 nt
	s_nop 0
	global_load_dwordx4 v[122:125], v[116:117], off offset:2048 nt
	s_waitcnt vmcnt(4)
	v_cvt_f32_f16_e32 v128, v118
	v_cvt_f32_f16_sdwa v129, v118 dst_sel:DWORD dst_unused:UNUSED_PAD src0_sel:WORD_1
	s_waitcnt vmcnt(0)
	v_cvt_f32_f16_e32 v126, v122
	v_cvt_f32_f16_sdwa v122, v122 dst_sel:DWORD dst_unused:UNUSED_PAD src0_sel:WORD_1
	v_cvt_f32_f16_e32 v118, v123
	v_mul_f32_e32 v126, 0xbfb8aa3b, v126
	v_mul_f32_e32 v122, 0xbfb8aa3b, v122
	v_mul_f32_e32 v118, 0xbfb8aa3b, v118
	v_exp_f32_e32 v122, v122
	v_exp_f32_e32 v118, v118
	v_exp_f32_e32 v126, v126
	v_add_f32_e32 v122, 1.0, v122
	v_add_f32_e32 v118, 1.0, v118
	v_rcp_f32_e32 v127, v122
	v_rcp_f32_e32 v122, v118
	v_cvt_f32_f16_sdwa v118, v123 dst_sel:DWORD dst_unused:UNUSED_PAD src0_sel:WORD_1
	v_add_f32_e32 v126, 1.0, v126
	v_rcp_f32_e32 v126, v126
	v_mul_f32_e32 v118, 0xbfb8aa3b, v118
	v_exp_f32_e32 v118, v118
	v_pk_fma_f32 v[94:95], v[94:95], v[126:127], v[128:129]
	v_add_f32_e32 v118, 1.0, v118
	v_rcp_f32_e32 v123, v118
	v_cvt_f32_f16_e32 v118, v119
	v_cvt_f32_f16_sdwa v119, v119 dst_sel:DWORD dst_unused:UNUSED_PAD src0_sel:WORD_1
	v_cvt_pk_f16_f32 v94, v94, v95
	v_pk_fma_f32 v[96:97], v[96:97], v[122:123], v[118:119]
	v_cvt_f32_f16_e32 v118, v124
	v_cvt_f32_f16_sdwa v119, v124 dst_sel:DWORD dst_unused:UNUSED_PAD src0_sel:WORD_1
	v_cvt_f32_f16_e32 v122, v120
	v_cvt_f32_f16_sdwa v123, v120 dst_sel:DWORD dst_unused:UNUSED_PAD src0_sel:WORD_1
	v_mul_f32_e32 v118, 0xbfb8aa3b, v118
	v_mul_f32_e32 v119, 0xbfb8aa3b, v119
	v_exp_f32_e32 v118, v118
	v_exp_f32_e32 v119, v119
	v_cvt_f32_f16_e32 v120, v121
	v_cvt_f32_f16_sdwa v121, v121 dst_sel:DWORD dst_unused:UNUSED_PAD src0_sel:WORD_1
	v_add_f32_e32 v118, 1.0, v118
	v_add_f32_e32 v119, 1.0, v119
	v_rcp_f32_e32 v118, v118
	v_rcp_f32_e32 v119, v119
	v_cvt_pk_f16_f32 v95, v96, v97
	v_pk_fma_f32 v[90:91], v[90:91], v[118:119], v[122:123]
	v_cvt_f32_f16_e32 v118, v125
	v_cvt_f32_f16_sdwa v119, v125 dst_sel:DWORD dst_unused:UNUSED_PAD src0_sel:WORD_1
	v_cvt_pk_f16_f32 v96, v90, v91
	v_lshl_add_u64 v[90:91], s[24:25], 0, v[114:115]
	v_mul_f32_e32 v118, 0xbfb8aa3b, v118
	v_mul_f32_e32 v119, 0xbfb8aa3b, v119
	v_exp_f32_e32 v118, v118
	v_exp_f32_e32 v119, v119
	v_lshl_add_u64 v[114:115], v[90:91], 0, v[152:153]
	v_add_f32_e32 v118, 1.0, v118
	v_add_f32_e32 v119, 1.0, v119
	v_rcp_f32_e32 v118, v118
	v_rcp_f32_e32 v119, v119
	s_nop 0
	v_pk_fma_f32 v[92:93], v[92:93], v[118:119], v[120:121]
	s_nop 0
	v_cvt_pk_f16_f32 v97, v92, v93
	global_load_dwordx4 v[90:93], v[112:113], off offset:2048 nt
	v_cvt_f32_f16_e32 v118, v106
	global_store_dwordx4 v[114:115], v[94:97], off
	global_load_dwordx4 v[94:97], v[116:117], off offset:2304 nt
	v_cvt_f32_f16_sdwa v119, v106 dst_sel:DWORD dst_unused:UNUSED_PAD src0_sel:WORD_1
	v_cvt_f32_f16_e32 v106, v107
	v_cvt_f32_f16_sdwa v107, v107 dst_sel:DWORD dst_unused:UNUSED_PAD src0_sel:WORD_1
	s_waitcnt vmcnt(0)
; __device__ __forceinline__ unsigned cvtpk(float lo, float hi) { f32x2_t v = {lo, hi}; f16x2_t b = __builtin_convertvector(v, f16x2_t); return __builtin_bit_cast(unsigned, b); }
; __device__ __forceinline__ float bflo(unsigned w) { const f16x2_t b = __builtin_bit_cast(f16x2_t, w); return (float)b[0]; }
; __device__ __forceinline__ float bfhi(unsigned w) { const f16x2_t b = __builtin_bit_cast(f16x2_t, w); return (float)b[1]; }
; __device__ __forceinline__ float sigmoidf_(float x) { return __builtin_amdgcn_rcpf(1.0f + __builtin_amdgcn_exp2f(-1.4426950408889634f * x)); }
;     __device__ __forceinline__ void operator()(const f32x4 (&acc)[2][2][4][2], const Unit& u, int wr, int wc, int fr, int fq) const {
;     ...
;                     for (int bj = 0; bj < 2; ++bj) { const int row = row0 + ai * HALF + (2 * mh + mm) * 16, col = col0 + bj * HALF;
;                         gv[mm][bj] = *(const u32x4*)(G + (size_t)row * 2048 + 1024 + col); sv[mm][bj] = *(const u32x4*)(scr + (size_t)row * 1024 + col); }
; #pragma unroll
;                 for (int mm = 0; mm < 2; ++mm)
; #pragma unroll
;                     for (int bj = 0; bj < 2; ++bj) { const int m = 2 * mh + mm; const int row = row0 + ai * HALF + m * 16, col = col0 + bj * HALF; const u32x4 g = gv[mm][bj]; const u32x4 sw = sv[mm][bj]; const f32x4 s0 = (f32x4){bflo(sw.x), bfhi(sw.x), bflo(sw.y), bfhi(sw.y)}, s1 = (f32x4){bflo(sw.z), bfhi(sw.z), bflo(sw.w), bfhi(sw.w)};
;                         f32x4 v0 = acc[ai][bj][m][0], v1 = acc[ai][bj][m][1];
;                         v0[0] = s0[0] + v0[0] * sigmoidf_(bflo(g.x)); v0[1] = s0[1] + v0[1] * sigmoidf_(bfhi(g.x)); v0[2] = s0[2] + v0[2] * sigmoidf_(bflo(g.y)); v0[3] = s0[3] + v0[3] * sigmoidf_(bfhi(g.y));
;                         v1[0] = s1[0] + v1[0] * sigmoidf_(bflo(g.z)); v1[1] = s1[1] + v1[1] * sigmoidf_(bfhi(g.z)); v1[2] = s1[2] + v1[2] * sigmoidf_(bflo(g.w)); v1[3] = s1[3] + v1[3] * sigmoidf_(bfhi(g.w));
;                         u32x4 w; w.x = cvtpk(v0[0], v0[1]); w.y = cvtpk(v0[2], v0[3]); w.z = cvtpk(v1[0], v1[1]); w.w = cvtpk(v1[2], v1[3]);
;                         *(u32x4*)(mrg + (size_t)row * 1024 + col) = w; }
	v_cvt_f32_f16_e32 v116, v94
	v_cvt_f32_f16_sdwa v94, v94 dst_sel:DWORD dst_unused:UNUSED_PAD src0_sel:WORD_1
	v_mul_f32_e32 v116, 0xbfb8aa3b, v116
	v_mul_f32_e32 v94, 0xbfb8aa3b, v94
	v_exp_f32_e32 v94, v94
	v_exp_f32_e32 v116, v116
	v_add_f32_e32 v94, 1.0, v94
	v_rcp_f32_e32 v117, v94
	v_cvt_f32_f16_e32 v94, v95
	v_cvt_f32_f16_sdwa v95, v95 dst_sel:DWORD dst_unused:UNUSED_PAD src0_sel:WORD_1
	v_add_f32_e32 v116, 1.0, v116
	v_rcp_f32_e32 v116, v116
	v_mul_f32_e32 v94, 0xbfb8aa3b, v94
	v_mul_f32_e32 v95, 0xbfb8aa3b, v95
	v_exp_f32_e32 v94, v94
	v_exp_f32_e32 v95, v95
	v_pk_fma_f32 v[86:87], v[86:87], v[116:117], v[118:119]
	v_add_f32_e32 v94, 1.0, v94
	v_add_f32_e32 v95, 1.0, v95
	v_rcp_f32_e32 v94, v94
	v_rcp_f32_e32 v95, v95
	v_cvt_pk_f16_f32 v86, v86, v87
	v_pk_fma_f32 v[88:89], v[88:89], v[94:95], v[106:107]
	v_cvt_f32_f16_e32 v94, v96
	v_cvt_f32_f16_sdwa v95, v96 dst_sel:DWORD dst_unused:UNUSED_PAD src0_sel:WORD_1
	v_cvt_f32_f16_e32 v106, v108
	v_cvt_f32_f16_sdwa v107, v108 dst_sel:DWORD dst_unused:UNUSED_PAD src0_sel:WORD_1
	v_mul_f32_e32 v94, 0xbfb8aa3b, v94
	v_mul_f32_e32 v95, 0xbfb8aa3b, v95
	v_exp_f32_e32 v94, v94
	v_exp_f32_e32 v95, v95
	v_cvt_f32_f16_e32 v96, v109
	v_cvt_pk_f16_f32 v87, v88, v89
	v_add_f32_e32 v94, 1.0, v94
	v_add_f32_e32 v95, 1.0, v95
	v_rcp_f32_e32 v94, v94
	v_rcp_f32_e32 v95, v95
	s_nop 0
	v_pk_fma_f32 v[82:83], v[82:83], v[94:95], v[106:107]
	v_cvt_f32_f16_e32 v94, v97
	v_cvt_f32_f16_sdwa v95, v97 dst_sel:DWORD dst_unused:UNUSED_PAD src0_sel:WORD_1
	v_cvt_f32_f16_sdwa v97, v109 dst_sel:DWORD dst_unused:UNUSED_PAD src0_sel:WORD_1
	v_cvt_pk_f16_f32 v88, v82, v83
	v_mul_f32_e32 v94, 0xbfb8aa3b, v94
	v_mul_f32_e32 v95, 0xbfb8aa3b, v95
	v_exp_f32_e32 v94, v94
	v_exp_f32_e32 v95, v95
	v_add_f32_e32 v94, 1.0, v94
	v_add_f32_e32 v95, 1.0, v95
	v_rcp_f32_e32 v94, v94
	v_rcp_f32_e32 v95, v95
	s_nop 0
	v_pk_fma_f32 v[84:85], v[84:85], v[94:95], v[96:97]
	s_nop 0
	v_cvt_pk_f16_f32 v89, v84, v85
	global_load_dwordx4 v[82:85], v[112:113], off offset:2304 nt
	s_nop 0
	global_store_dwordx4 v[114:115], v[86:89], off offset:256
	s_nop 1
	v_cvt_f32_f16_e32 v86, v90
	v_cvt_f32_f16_sdwa v87, v90 dst_sel:DWORD dst_unused:UNUSED_PAD src0_sel:WORD_1
	v_cvt_f32_f16_e32 v88, v102
	v_cvt_f32_f16_sdwa v89, v102 dst_sel:DWORD dst_unused:UNUSED_PAD src0_sel:WORD_1
	v_mul_f32_e32 v86, 0xbfb8aa3b, v86
	v_mul_f32_e32 v87, 0xbfb8aa3b, v87
	v_exp_f32_e32 v86, v86
	v_exp_f32_e32 v87, v87
	v_add_f32_e32 v86, 1.0, v86
	v_add_f32_e32 v87, 1.0, v87
	v_rcp_f32_e32 v86, v86
	v_rcp_f32_e32 v87, v87
	s_nop 0
	v_pk_fma_f32 v[78:79], v[78:79], v[86:87], v[88:89]
	v_cvt_f32_f16_e32 v86, v91
	v_cvt_f32_f16_sdwa v87, v91 dst_sel:DWORD dst_unused:UNUSED_PAD src0_sel:WORD_1
	v_cvt_f32_f16_e32 v88, v103
	v_cvt_f32_f16_sdwa v89, v103 dst_sel:DWORD dst_unused:UNUSED_PAD src0_sel:WORD_1
	v_mul_f32_e32 v86, 0xbfb8aa3b, v86
	v_mul_f32_e32 v87, 0xbfb8aa3b, v87
	v_exp_f32_e32 v86, v86
	v_exp_f32_e32 v87, v87
	v_add_f32_e32 v86, 1.0, v86
	v_add_f32_e32 v87, 1.0, v87
	v_rcp_f32_e32 v86, v86
	v_rcp_f32_e32 v87, v87
	s_nop 0
	v_pk_fma_f32 v[80:81], v[80:81], v[86:87], v[88:89]
	v_cvt_f32_f16_e32 v86, v92
	v_cvt_f32_f16_sdwa v87, v92 dst_sel:DWORD dst_unused:UNUSED_PAD src0_sel:WORD_1
	v_cvt_f32_f16_e32 v88, v104
	v_cvt_f32_f16_sdwa v89, v104 dst_sel:DWORD dst_unused:UNUSED_PAD src0_sel:WORD_1
	v_mul_f32_e32 v86, 0xbfb8aa3b, v86
	v_mul_f32_e32 v87, 0xbfb8aa3b, v87
	v_exp_f32_e32 v86, v86
	v_exp_f32_e32 v87, v87
	v_add_f32_e32 v86, 1.0, v86
	v_add_f32_e32 v87, 1.0, v87
	v_rcp_f32_e32 v86, v86
	v_rcp_f32_e32 v87, v87
	s_nop 0
	v_pk_fma_f32 v[74:75], v[74:75], v[86:87], v[88:89]
	v_cvt_f32_f16_e32 v86, v93
	v_cvt_f32_f16_sdwa v87, v93 dst_sel:DWORD dst_unused:UNUSED_PAD src0_sel:WORD_1
	v_cvt_f32_f16_e32 v88, v105
	v_cvt_f32_f16_sdwa v89, v105 dst_sel:DWORD dst_unused:UNUSED_PAD src0_sel:WORD_1
	v_mul_f32_e32 v86, 0xbfb8aa3b, v86
	v_mul_f32_e32 v87, 0xbfb8aa3b, v87
	v_exp_f32_e32 v86, v86
	v_exp_f32_e32 v87, v87
	v_add_f32_e32 v86, 1.0, v86
	v_add_f32_e32 v87, 1.0, v87
	v_rcp_f32_e32 v86, v86
	v_rcp_f32_e32 v87, v87
	s_nop 0
	v_pk_fma_f32 v[86:87], v[76:77], v[86:87], v[88:89]
	v_cvt_pk_f16_f32 v76, v78, v79
	v_cvt_pk_f16_f32 v78, v74, v75
	v_lshl_add_u64 v[74:75], s[24:25], 0, v[110:111]
	v_cvt_pk_f16_f32 v77, v80, v81
	v_cvt_pk_f16_f32 v79, v86, v87
	v_lshl_add_u64 v[74:75], v[74:75], 0, v[152:153]
	global_store_dwordx4 v[74:75], v[76:79], off
	s_waitcnt vmcnt(2)
; __device__ __forceinline__ unsigned cvtpk(float lo, float hi) { f32x2_t v = {lo, hi}; f16x2_t b = __builtin_convertvector(v, f16x2_t); return __builtin_bit_cast(unsigned, b); }
; __device__ __forceinline__ float bflo(unsigned w) { const f16x2_t b = __builtin_bit_cast(f16x2_t, w); return (float)b[0]; }
; __device__ __forceinline__ float bfhi(unsigned w) { const f16x2_t b = __builtin_bit_cast(f16x2_t, w); return (float)b[1]; }
; __device__ __forceinline__ float sigmoidf_(float x) { return __builtin_amdgcn_rcpf(1.0f + __builtin_amdgcn_exp2f(-1.4426950408889634f * x)); }
;     __device__ __forceinline__ void operator()(const f32x4 (&acc)[2][2][4][2], const Unit& u, int wr, int wc, int fr, int fq) const {
;     ...
;             for (int mh = 0; mh < 2; ++mh) { u32x4 gv[2][2]; u32x4 sv[2][2];
; #pragma unroll
;                 for (int mm = 0; mm < 2; ++mm)
; #pragma unroll
;                     for (int bj = 0; bj < 2; ++bj) { const int row = row0 + ai * HALF + (2 * mh + mm) * 16, col = col0 + bj * HALF;
;                         gv[mm][bj] = *(const u32x4*)(G + (size_t)row * 2048 + 1024 + col); sv[mm][bj] = *(const u32x4*)(scr + (size_t)row * 1024 + col); }
; #pragma unroll
;                 for (int mm = 0; mm < 2; ++mm)
; #pragma unroll
;                     for (int bj = 0; bj < 2; ++bj) { const int m = 2 * mh + mm; const int row = row0 + ai * HALF + m * 16, col = col0 + bj * HALF; const u32x4 g = gv[mm][bj]; const u32x4 sw = sv[mm][bj]; const f32x4 s0 = (f32x4){bflo(sw.x), bfhi(sw.x), bflo(sw.y), bfhi(sw.y)}, s1 = (f32x4){bflo(sw.z), bfhi(sw.z), bflo(sw.w), bfhi(sw.w)};
;                         f32x4 v0 = acc[ai][bj][m][0], v1 = acc[ai][bj][m][1];
;                         v0[0] = s0[0] + v0[0] * sigmoidf_(bflo(g.x)); v0[1] = s0[1] + v0[1] * sigmoidf_(bfhi(g.x)); v0[2] = s0[2] + v0[2] * sigmoidf_(bflo(g.y)); v0[3] = s0[3] + v0[3] * sigmoidf_(bfhi(g.y));
;                         v1[0] = s1[0] + v1[0] * sigmoidf_(bflo(g.z)); v1[1] = s1[1] + v1[1] * sigmoidf_(bfhi(g.z)); v1[2] = s1[2] + v1[2] * sigmoidf_(bflo(g.w)); v1[3] = s1[3] + v1[3] * sigmoidf_(bfhi(g.w));
;                         u32x4 w; w.x = cvtpk(v0[0], v0[1]); w.y = cvtpk(v0[2], v0[3]); w.z = cvtpk(v1[0], v1[1]); w.w = cvtpk(v1[2], v1[3]);
;                         *(u32x4*)(mrg + (size_t)row * 1024 + col) = w; }
;                 asm volatile("" ::: "memory"); }
	s_nop 0
	v_cvt_f32_f16_e32 v76, v82
	v_cvt_f32_f16_sdwa v77, v82 dst_sel:DWORD dst_unused:UNUSED_PAD src0_sel:WORD_1
	v_cvt_f32_f16_e32 v78, v98
	v_cvt_f32_f16_sdwa v79, v98 dst_sel:DWORD dst_unused:UNUSED_PAD src0_sel:WORD_1
	v_mul_f32_e32 v76, 0xbfb8aa3b, v76
	v_mul_f32_e32 v77, 0xbfb8aa3b, v77
	v_exp_f32_e32 v76, v76
	v_exp_f32_e32 v77, v77
	v_add_f32_e32 v76, 1.0, v76
	v_add_f32_e32 v77, 1.0, v77
	v_rcp_f32_e32 v76, v76
	v_rcp_f32_e32 v77, v77
	s_nop 0
	v_pk_fma_f32 v[70:71], v[70:71], v[76:77], v[78:79]
	v_cvt_f32_f16_e32 v76, v83
	v_cvt_f32_f16_sdwa v77, v83 dst_sel:DWORD dst_unused:UNUSED_PAD src0_sel:WORD_1
	v_cvt_f32_f16_e32 v78, v99
	v_cvt_f32_f16_sdwa v79, v99 dst_sel:DWORD dst_unused:UNUSED_PAD src0_sel:WORD_1
	v_mul_f32_e32 v76, 0xbfb8aa3b, v76
	v_mul_f32_e32 v77, 0xbfb8aa3b, v77
	v_exp_f32_e32 v76, v76
	v_exp_f32_e32 v77, v77
	v_add_f32_e32 v76, 1.0, v76
	v_add_f32_e32 v77, 1.0, v77
	v_rcp_f32_e32 v76, v76
	v_rcp_f32_e32 v77, v77
	s_nop 0
	v_pk_fma_f32 v[72:73], v[72:73], v[76:77], v[78:79]
	v_cvt_f32_f16_e32 v76, v84
	v_cvt_f32_f16_sdwa v77, v84 dst_sel:DWORD dst_unused:UNUSED_PAD src0_sel:WORD_1
	v_cvt_f32_f16_e32 v78, v100
	v_cvt_f32_f16_sdwa v79, v100 dst_sel:DWORD dst_unused:UNUSED_PAD src0_sel:WORD_1
	v_mul_f32_e32 v76, 0xbfb8aa3b, v76
	v_mul_f32_e32 v77, 0xbfb8aa3b, v77
	v_exp_f32_e32 v76, v76
	v_exp_f32_e32 v77, v77
	v_add_f32_e32 v76, 1.0, v76
	v_add_f32_e32 v77, 1.0, v77
	v_rcp_f32_e32 v76, v76
	v_rcp_f32_e32 v77, v77
	s_nop 0
	v_pk_fma_f32 v[76:77], v[66:67], v[76:77], v[78:79]
	v_cvt_f32_f16_e32 v66, v85
	v_cvt_f32_f16_sdwa v67, v85 dst_sel:DWORD dst_unused:UNUSED_PAD src0_sel:WORD_1
	v_cvt_f32_f16_e32 v78, v101
	v_cvt_f32_f16_sdwa v79, v101 dst_sel:DWORD dst_unused:UNUSED_PAD src0_sel:WORD_1
	v_mul_f32_e32 v66, 0xbfb8aa3b, v66
	v_mul_f32_e32 v67, 0xbfb8aa3b, v67
	v_exp_f32_e32 v66, v66
	v_exp_f32_e32 v67, v67
	v_add_f32_e32 v66, 1.0, v66
	v_add_f32_e32 v67, 1.0, v67
	v_rcp_f32_e32 v66, v66
	v_rcp_f32_e32 v67, v67
	s_nop 0
	v_pk_fma_f32 v[78:79], v[68:69], v[66:67], v[78:79]
	v_cvt_pk_f16_f32 v66, v70, v71
	v_cvt_pk_f16_f32 v67, v72, v73
	v_cvt_pk_f16_f32 v68, v76, v77
	v_cvt_pk_f16_f32 v69, v78, v79
	global_store_dwordx4 v[74:75], v[66:69], off offset:256
	s_nop 1
	v_add_u32_e32 v66, 0x80, v154
	v_ashrrev_i32_e32 v67, 31, v66
	v_lshlrev_b64 v[82:83], 11, v[66:67]
	v_lshlrev_b64 v[68:69], 12, v[66:67]
	v_lshl_add_u64 v[66:67], s[74:75], 0, v[82:83]
	v_lshl_add_u64 v[66:67], v[66:67], 0, v[152:153]
	global_load_dwordx4 v[86:89], v[66:67], off nt
	global_load_dwordx4 v[74:77], v[66:67], off offset:256 nt
	v_add_u32_e32 v66, 0x90, v154
	v_ashrrev_i32_e32 v67, 31, v66
	v_lshl_add_u64 v[68:69], s[14:15], 0, v[68:69]
	v_lshlrev_b64 v[78:79], 11, v[66:67]
	v_lshl_add_u64 v[84:85], v[68:69], 0, v[152:153]
	v_lshlrev_b64 v[68:69], 12, v[66:67]
	v_lshl_add_u64 v[66:67], s[74:75], 0, v[78:79]
	v_lshl_add_u64 v[68:69], s[14:15], 0, v[68:69]
	v_lshl_add_u64 v[66:67], v[66:67], 0, v[152:153]
	v_lshl_add_u64 v[80:81], v[68:69], 0, v[152:153]
	global_load_dwordx4 v[70:73], v[66:67], off nt
	s_nop 0
	global_load_dwordx4 v[66:69], v[66:67], off offset:256 nt
	s_nop 0
	global_load_dwordx4 v[90:93], v[84:85], off offset:2048 nt
	s_waitcnt vmcnt(4)
	v_cvt_f32_f16_e32 v96, v86
	v_cvt_f32_f16_sdwa v97, v86 dst_sel:DWORD dst_unused:UNUSED_PAD src0_sel:WORD_1
	s_waitcnt vmcnt(0)
	v_cvt_f32_f16_e32 v94, v90
	v_cvt_f32_f16_sdwa v90, v90 dst_sel:DWORD dst_unused:UNUSED_PAD src0_sel:WORD_1
	v_cvt_f32_f16_e32 v86, v91
	v_mul_f32_e32 v94, 0xbfb8aa3b, v94
	v_mul_f32_e32 v90, 0xbfb8aa3b, v90
	v_mul_f32_e32 v86, 0xbfb8aa3b, v86
	v_exp_f32_e32 v90, v90
	v_exp_f32_e32 v86, v86
	v_exp_f32_e32 v94, v94
	v_add_f32_e32 v90, 1.0, v90
	v_add_f32_e32 v86, 1.0, v86
	v_rcp_f32_e32 v95, v90
	v_rcp_f32_e32 v90, v86
	v_cvt_f32_f16_sdwa v86, v91 dst_sel:DWORD dst_unused:UNUSED_PAD src0_sel:WORD_1
	v_add_f32_e32 v94, 1.0, v94
	v_rcp_f32_e32 v94, v94
	v_mul_f32_e32 v86, 0xbfb8aa3b, v86
	v_exp_f32_e32 v86, v86
	v_pk_fma_f32 v[62:63], v[62:63], v[94:95], v[96:97]
	v_add_f32_e32 v86, 1.0, v86
	v_rcp_f32_e32 v91, v86
	v_cvt_f32_f16_e32 v86, v87
	v_cvt_f32_f16_sdwa v87, v87 dst_sel:DWORD dst_unused:UNUSED_PAD src0_sel:WORD_1
	v_cvt_pk_f16_f32 v62, v62, v63
	v_pk_fma_f32 v[64:65], v[64:65], v[90:91], v[86:87]
	v_cvt_f32_f16_e32 v86, v92
	v_cvt_f32_f16_sdwa v87, v92 dst_sel:DWORD dst_unused:UNUSED_PAD src0_sel:WORD_1
	v_cvt_f32_f16_e32 v90, v88
	v_cvt_f32_f16_sdwa v91, v88 dst_sel:DWORD dst_unused:UNUSED_PAD src0_sel:WORD_1
	v_mul_f32_e32 v86, 0xbfb8aa3b, v86
	v_mul_f32_e32 v87, 0xbfb8aa3b, v87
	v_exp_f32_e32 v86, v86
	v_exp_f32_e32 v87, v87
	v_cvt_f32_f16_e32 v88, v89
	v_cvt_f32_f16_sdwa v89, v89 dst_sel:DWORD dst_unused:UNUSED_PAD src0_sel:WORD_1
	v_add_f32_e32 v86, 1.0, v86
	v_add_f32_e32 v87, 1.0, v87
	v_rcp_f32_e32 v86, v86
	v_rcp_f32_e32 v87, v87
	v_cvt_pk_f16_f32 v63, v64, v65
	v_pk_fma_f32 v[58:59], v[58:59], v[86:87], v[90:91]
	v_cvt_f32_f16_e32 v86, v93
	v_cvt_f32_f16_sdwa v87, v93 dst_sel:DWORD dst_unused:UNUSED_PAD src0_sel:WORD_1
	v_cvt_pk_f16_f32 v64, v58, v59
	v_lshl_add_u64 v[58:59], s[24:25], 0, v[82:83]
	v_mul_f32_e32 v86, 0xbfb8aa3b, v86
	v_mul_f32_e32 v87, 0xbfb8aa3b, v87
	v_exp_f32_e32 v86, v86
	v_exp_f32_e32 v87, v87
	v_lshl_add_u64 v[82:83], v[58:59], 0, v[152:153]
	v_add_f32_e32 v86, 1.0, v86
	v_add_f32_e32 v87, 1.0, v87
	v_rcp_f32_e32 v86, v86
	v_rcp_f32_e32 v87, v87
	s_nop 0
	v_pk_fma_f32 v[60:61], v[60:61], v[86:87], v[88:89]
	s_nop 0
	v_cvt_pk_f16_f32 v65, v60, v61
	global_load_dwordx4 v[58:61], v[80:81], off offset:2048 nt
	v_cvt_f32_f16_e32 v86, v74
	global_store_dwordx4 v[82:83], v[62:65], off
	global_load_dwordx4 v[62:65], v[84:85], off offset:2304 nt
	v_cvt_f32_f16_sdwa v87, v74 dst_sel:DWORD dst_unused:UNUSED_PAD src0_sel:WORD_1
	v_cvt_f32_f16_e32 v74, v75
	v_cvt_f32_f16_sdwa v75, v75 dst_sel:DWORD dst_unused:UNUSED_PAD src0_sel:WORD_1
	s_waitcnt vmcnt(0)
; __device__ __forceinline__ unsigned cvtpk(float lo, float hi) { f32x2_t v = {lo, hi}; f16x2_t b = __builtin_convertvector(v, f16x2_t); return __builtin_bit_cast(unsigned, b); }
; __device__ __forceinline__ float bflo(unsigned w) { const f16x2_t b = __builtin_bit_cast(f16x2_t, w); return (float)b[0]; }
; __device__ __forceinline__ float bfhi(unsigned w) { const f16x2_t b = __builtin_bit_cast(f16x2_t, w); return (float)b[1]; }
; __device__ __forceinline__ float sigmoidf_(float x) { return __builtin_amdgcn_rcpf(1.0f + __builtin_amdgcn_exp2f(-1.4426950408889634f * x)); }
;     __device__ __forceinline__ void operator()(const f32x4 (&acc)[2][2][4][2], const Unit& u, int wr, int wc, int fr, int fq) const {
;     ...
;                     for (int bj = 0; bj < 2; ++bj) { const int row = row0 + ai * HALF + (2 * mh + mm) * 16, col = col0 + bj * HALF;
;                         gv[mm][bj] = *(const u32x4*)(G + (size_t)row * 2048 + 1024 + col); sv[mm][bj] = *(const u32x4*)(scr + (size_t)row * 1024 + col); }
; #pragma unroll
;                 for (int mm = 0; mm < 2; ++mm)
; #pragma unroll
;                     for (int bj = 0; bj < 2; ++bj) { const int m = 2 * mh + mm; const int row = row0 + ai * HALF + m * 16, col = col0 + bj * HALF; const u32x4 g = gv[mm][bj]; const u32x4 sw = sv[mm][bj]; const f32x4 s0 = (f32x4){bflo(sw.x), bfhi(sw.x), bflo(sw.y), bfhi(sw.y)}, s1 = (f32x4){bflo(sw.z), bfhi(sw.z), bflo(sw.w), bfhi(sw.w)};
;                         f32x4 v0 = acc[ai][bj][m][0], v1 = acc[ai][bj][m][1];
;                         v0[0] = s0[0] + v0[0] * sigmoidf_(bflo(g.x)); v0[1] = s0[1] + v0[1] * sigmoidf_(bfhi(g.x)); v0[2] = s0[2] + v0[2] * sigmoidf_(bflo(g.y)); v0[3] = s0[3] + v0[3] * sigmoidf_(bfhi(g.y));
;                         v1[0] = s1[0] + v1[0] * sigmoidf_(bflo(g.z)); v1[1] = s1[1] + v1[1] * sigmoidf_(bfhi(g.z)); v1[2] = s1[2] + v1[2] * sigmoidf_(bflo(g.w)); v1[3] = s1[3] + v1[3] * sigmoidf_(bfhi(g.w));
;                         u32x4 w; w.x = cvtpk(v0[0], v0[1]); w.y = cvtpk(v0[2], v0[3]); w.z = cvtpk(v1[0], v1[1]); w.w = cvtpk(v1[2], v1[3]);
;                         *(u32x4*)(mrg + (size_t)row * 1024 + col) = w; }
	v_cvt_f32_f16_e32 v84, v62
	v_cvt_f32_f16_sdwa v62, v62 dst_sel:DWORD dst_unused:UNUSED_PAD src0_sel:WORD_1
	v_mul_f32_e32 v84, 0xbfb8aa3b, v84
	v_mul_f32_e32 v62, 0xbfb8aa3b, v62
	v_exp_f32_e32 v62, v62
	v_exp_f32_e32 v84, v84
	v_add_f32_e32 v62, 1.0, v62
	v_rcp_f32_e32 v85, v62
	v_cvt_f32_f16_e32 v62, v63
	v_cvt_f32_f16_sdwa v63, v63 dst_sel:DWORD dst_unused:UNUSED_PAD src0_sel:WORD_1
	v_add_f32_e32 v84, 1.0, v84
	v_rcp_f32_e32 v84, v84
	v_mul_f32_e32 v62, 0xbfb8aa3b, v62
	v_mul_f32_e32 v63, 0xbfb8aa3b, v63
	v_exp_f32_e32 v62, v62
	v_exp_f32_e32 v63, v63
	v_pk_fma_f32 v[54:55], v[54:55], v[84:85], v[86:87]
	v_add_f32_e32 v62, 1.0, v62
	v_add_f32_e32 v63, 1.0, v63
	v_rcp_f32_e32 v62, v62
	v_rcp_f32_e32 v63, v63
	v_cvt_pk_f16_f32 v54, v54, v55
	v_pk_fma_f32 v[56:57], v[56:57], v[62:63], v[74:75]
	v_cvt_f32_f16_e32 v62, v64
	v_cvt_f32_f16_sdwa v63, v64 dst_sel:DWORD dst_unused:UNUSED_PAD src0_sel:WORD_1
	v_cvt_f32_f16_e32 v74, v76
	v_cvt_f32_f16_sdwa v75, v76 dst_sel:DWORD dst_unused:UNUSED_PAD src0_sel:WORD_1
	v_mul_f32_e32 v62, 0xbfb8aa3b, v62
	v_mul_f32_e32 v63, 0xbfb8aa3b, v63
	v_exp_f32_e32 v62, v62
	v_exp_f32_e32 v63, v63
	v_cvt_f32_f16_e32 v64, v77
	v_cvt_pk_f16_f32 v55, v56, v57
	v_add_f32_e32 v62, 1.0, v62
	v_add_f32_e32 v63, 1.0, v63
	v_rcp_f32_e32 v62, v62
	v_rcp_f32_e32 v63, v63
	s_nop 0
	v_pk_fma_f32 v[50:51], v[50:51], v[62:63], v[74:75]
	v_cvt_f32_f16_e32 v62, v65
	v_cvt_f32_f16_sdwa v63, v65 dst_sel:DWORD dst_unused:UNUSED_PAD src0_sel:WORD_1
	v_cvt_f32_f16_sdwa v65, v77 dst_sel:DWORD dst_unused:UNUSED_PAD src0_sel:WORD_1
	v_cvt_pk_f16_f32 v56, v50, v51
	v_mul_f32_e32 v62, 0xbfb8aa3b, v62
	v_mul_f32_e32 v63, 0xbfb8aa3b, v63
	v_exp_f32_e32 v62, v62
	v_exp_f32_e32 v63, v63
	v_add_f32_e32 v62, 1.0, v62
	v_add_f32_e32 v63, 1.0, v63
	v_rcp_f32_e32 v62, v62
	v_rcp_f32_e32 v63, v63
	s_nop 0
	v_pk_fma_f32 v[52:53], v[52:53], v[62:63], v[64:65]
	s_nop 0
	v_cvt_pk_f16_f32 v57, v52, v53
	global_load_dwordx4 v[50:53], v[80:81], off offset:2304 nt
	s_nop 0
	global_store_dwordx4 v[82:83], v[54:57], off offset:256
	s_nop 1
	v_cvt_f32_f16_e32 v54, v58
	v_cvt_f32_f16_sdwa v55, v58 dst_sel:DWORD dst_unused:UNUSED_PAD src0_sel:WORD_1
	v_cvt_f32_f16_e32 v56, v70
	v_cvt_f32_f16_sdwa v57, v70 dst_sel:DWORD dst_unused:UNUSED_PAD src0_sel:WORD_1
	v_mul_f32_e32 v54, 0xbfb8aa3b, v54
	v_mul_f32_e32 v55, 0xbfb8aa3b, v55
	v_exp_f32_e32 v54, v54
	v_exp_f32_e32 v55, v55
	v_add_f32_e32 v54, 1.0, v54
	v_add_f32_e32 v55, 1.0, v55
	v_rcp_f32_e32 v54, v54
	v_rcp_f32_e32 v55, v55
	s_nop 0
	v_pk_fma_f32 v[46:47], v[46:47], v[54:55], v[56:57]
	v_cvt_f32_f16_e32 v54, v59
	v_cvt_f32_f16_sdwa v55, v59 dst_sel:DWORD dst_unused:UNUSED_PAD src0_sel:WORD_1
	v_cvt_f32_f16_e32 v56, v71
	v_cvt_f32_f16_sdwa v57, v71 dst_sel:DWORD dst_unused:UNUSED_PAD src0_sel:WORD_1
	v_mul_f32_e32 v54, 0xbfb8aa3b, v54
	v_mul_f32_e32 v55, 0xbfb8aa3b, v55
	v_exp_f32_e32 v54, v54
	v_exp_f32_e32 v55, v55
	v_add_f32_e32 v54, 1.0, v54
	v_add_f32_e32 v55, 1.0, v55
	v_rcp_f32_e32 v54, v54
	v_rcp_f32_e32 v55, v55
	s_nop 0
	v_pk_fma_f32 v[48:49], v[48:49], v[54:55], v[56:57]
	v_cvt_f32_f16_e32 v54, v60
	v_cvt_f32_f16_sdwa v55, v60 dst_sel:DWORD dst_unused:UNUSED_PAD src0_sel:WORD_1
	v_cvt_f32_f16_e32 v56, v72
	v_cvt_f32_f16_sdwa v57, v72 dst_sel:DWORD dst_unused:UNUSED_PAD src0_sel:WORD_1
	v_mul_f32_e32 v54, 0xbfb8aa3b, v54
	v_mul_f32_e32 v55, 0xbfb8aa3b, v55
	v_exp_f32_e32 v54, v54
	v_exp_f32_e32 v55, v55
	v_add_f32_e32 v54, 1.0, v54
	v_add_f32_e32 v55, 1.0, v55
	v_rcp_f32_e32 v54, v54
	v_rcp_f32_e32 v55, v55
	s_nop 0
	v_pk_fma_f32 v[42:43], v[42:43], v[54:55], v[56:57]
	v_cvt_f32_f16_e32 v54, v61
	v_cvt_f32_f16_sdwa v55, v61 dst_sel:DWORD dst_unused:UNUSED_PAD src0_sel:WORD_1
	v_cvt_f32_f16_e32 v56, v73
	v_cvt_f32_f16_sdwa v57, v73 dst_sel:DWORD dst_unused:UNUSED_PAD src0_sel:WORD_1
	v_mul_f32_e32 v54, 0xbfb8aa3b, v54
	v_mul_f32_e32 v55, 0xbfb8aa3b, v55
	v_exp_f32_e32 v54, v54
	v_exp_f32_e32 v55, v55
	v_add_f32_e32 v54, 1.0, v54
	v_add_f32_e32 v55, 1.0, v55
	v_rcp_f32_e32 v54, v54
	v_rcp_f32_e32 v55, v55
	s_nop 0
	v_pk_fma_f32 v[54:55], v[44:45], v[54:55], v[56:57]
	v_cvt_pk_f16_f32 v44, v46, v47
	v_cvt_pk_f16_f32 v46, v42, v43
	v_lshl_add_u64 v[42:43], s[24:25], 0, v[78:79]
	v_cvt_pk_f16_f32 v45, v48, v49
	v_cvt_pk_f16_f32 v47, v54, v55
	v_lshl_add_u64 v[42:43], v[42:43], 0, v[152:153]
	global_store_dwordx4 v[42:43], v[44:47], off
	s_waitcnt vmcnt(2)
; __device__ __forceinline__ unsigned cvtpk(float lo, float hi) { f32x2_t v = {lo, hi}; f16x2_t b = __builtin_convertvector(v, f16x2_t); return __builtin_bit_cast(unsigned, b); }
; __device__ __forceinline__ float bflo(unsigned w) { const f16x2_t b = __builtin_bit_cast(f16x2_t, w); return (float)b[0]; }
; __device__ __forceinline__ float bfhi(unsigned w) { const f16x2_t b = __builtin_bit_cast(f16x2_t, w); return (float)b[1]; }
; __device__ __forceinline__ float sigmoidf_(float x) { return __builtin_amdgcn_rcpf(1.0f + __builtin_amdgcn_exp2f(-1.4426950408889634f * x)); }
;     __device__ __forceinline__ void operator()(const f32x4 (&acc)[2][2][4][2], const Unit& u, int wr, int wc, int fr, int fq) const {
;     ...
;             for (int mh = 0; mh < 2; ++mh) { u32x4 gv[2][2]; u32x4 sv[2][2];
; #pragma unroll
;                 for (int mm = 0; mm < 2; ++mm)
; #pragma unroll
;                     for (int bj = 0; bj < 2; ++bj) { const int row = row0 + ai * HALF + (2 * mh + mm) * 16, col = col0 + bj * HALF;
;                         gv[mm][bj] = *(const u32x4*)(G + (size_t)row * 2048 + 1024 + col); sv[mm][bj] = *(const u32x4*)(scr + (size_t)row * 1024 + col); }
; #pragma unroll
;                 for (int mm = 0; mm < 2; ++mm)
; #pragma unroll
;                     for (int bj = 0; bj < 2; ++bj) { const int m = 2 * mh + mm; const int row = row0 + ai * HALF + m * 16, col = col0 + bj * HALF; const u32x4 g = gv[mm][bj]; const u32x4 sw = sv[mm][bj]; const f32x4 s0 = (f32x4){bflo(sw.x), bfhi(sw.x), bflo(sw.y), bfhi(sw.y)}, s1 = (f32x4){bflo(sw.z), bfhi(sw.z), bflo(sw.w), bfhi(sw.w)};
;                         f32x4 v0 = acc[ai][bj][m][0], v1 = acc[ai][bj][m][1];
;                         v0[0] = s0[0] + v0[0] * sigmoidf_(bflo(g.x)); v0[1] = s0[1] + v0[1] * sigmoidf_(bfhi(g.x)); v0[2] = s0[2] + v0[2] * sigmoidf_(bflo(g.y)); v0[3] = s0[3] + v0[3] * sigmoidf_(bfhi(g.y));
;                         v1[0] = s1[0] + v1[0] * sigmoidf_(bflo(g.z)); v1[1] = s1[1] + v1[1] * sigmoidf_(bfhi(g.z)); v1[2] = s1[2] + v1[2] * sigmoidf_(bflo(g.w)); v1[3] = s1[3] + v1[3] * sigmoidf_(bfhi(g.w));
;                         u32x4 w; w.x = cvtpk(v0[0], v0[1]); w.y = cvtpk(v0[2], v0[3]); w.z = cvtpk(v1[0], v1[1]); w.w = cvtpk(v1[2], v1[3]);
;                         *(u32x4*)(mrg + (size_t)row * 1024 + col) = w; }
;                 asm volatile("" ::: "memory"); }
	s_nop 0
	v_cvt_f32_f16_e32 v44, v50
	v_cvt_f32_f16_sdwa v45, v50 dst_sel:DWORD dst_unused:UNUSED_PAD src0_sel:WORD_1
	v_cvt_f32_f16_e32 v46, v66
	v_cvt_f32_f16_sdwa v47, v66 dst_sel:DWORD dst_unused:UNUSED_PAD src0_sel:WORD_1
	v_mul_f32_e32 v44, 0xbfb8aa3b, v44
	v_mul_f32_e32 v45, 0xbfb8aa3b, v45
	v_exp_f32_e32 v44, v44
	v_exp_f32_e32 v45, v45
	v_add_f32_e32 v44, 1.0, v44
	v_add_f32_e32 v45, 1.0, v45
	v_rcp_f32_e32 v44, v44
	v_rcp_f32_e32 v45, v45
	s_nop 0
	v_pk_fma_f32 v[38:39], v[38:39], v[44:45], v[46:47]
	v_cvt_f32_f16_e32 v44, v51
	v_cvt_f32_f16_sdwa v45, v51 dst_sel:DWORD dst_unused:UNUSED_PAD src0_sel:WORD_1
	v_cvt_f32_f16_e32 v46, v67
	v_cvt_f32_f16_sdwa v47, v67 dst_sel:DWORD dst_unused:UNUSED_PAD src0_sel:WORD_1
	v_mul_f32_e32 v44, 0xbfb8aa3b, v44
	v_mul_f32_e32 v45, 0xbfb8aa3b, v45
	v_exp_f32_e32 v44, v44
	v_exp_f32_e32 v45, v45
	v_add_f32_e32 v44, 1.0, v44
	v_add_f32_e32 v45, 1.0, v45
	v_rcp_f32_e32 v44, v44
	v_rcp_f32_e32 v45, v45
	s_nop 0
	v_pk_fma_f32 v[40:41], v[40:41], v[44:45], v[46:47]
	v_cvt_f32_f16_e32 v44, v52
	v_cvt_f32_f16_sdwa v45, v52 dst_sel:DWORD dst_unused:UNUSED_PAD src0_sel:WORD_1
	v_cvt_f32_f16_e32 v46, v68
	v_cvt_f32_f16_sdwa v47, v68 dst_sel:DWORD dst_unused:UNUSED_PAD src0_sel:WORD_1
	v_mul_f32_e32 v44, 0xbfb8aa3b, v44
	v_mul_f32_e32 v45, 0xbfb8aa3b, v45
	v_exp_f32_e32 v44, v44
	v_exp_f32_e32 v45, v45
	v_add_f32_e32 v44, 1.0, v44
	v_add_f32_e32 v45, 1.0, v45
	v_rcp_f32_e32 v44, v44
	v_rcp_f32_e32 v45, v45
	s_nop 0
	v_pk_fma_f32 v[44:45], v[34:35], v[44:45], v[46:47]
	v_cvt_f32_f16_e32 v34, v53
	v_cvt_f32_f16_sdwa v35, v53 dst_sel:DWORD dst_unused:UNUSED_PAD src0_sel:WORD_1
	v_cvt_f32_f16_e32 v46, v69
	v_cvt_f32_f16_sdwa v47, v69 dst_sel:DWORD dst_unused:UNUSED_PAD src0_sel:WORD_1
	v_mul_f32_e32 v34, 0xbfb8aa3b, v34
	v_mul_f32_e32 v35, 0xbfb8aa3b, v35
	v_exp_f32_e32 v34, v34
	v_exp_f32_e32 v35, v35
	v_add_f32_e32 v34, 1.0, v34
	v_add_f32_e32 v35, 1.0, v35
	v_rcp_f32_e32 v34, v34
	v_rcp_f32_e32 v35, v35
	s_nop 0
	v_pk_fma_f32 v[46:47], v[36:37], v[34:35], v[46:47]
	v_cvt_pk_f16_f32 v34, v38, v39
	v_cvt_pk_f16_f32 v35, v40, v41
	v_cvt_pk_f16_f32 v36, v44, v45
	v_cvt_pk_f16_f32 v37, v46, v47
	global_store_dwordx4 v[42:43], v[34:37], off offset:256
	s_nop 1
	v_add_u32_e32 v34, 0xa0, v154
	v_ashrrev_i32_e32 v35, 31, v34
	v_lshlrev_b64 v[50:51], 11, v[34:35]
	v_lshlrev_b64 v[36:37], 12, v[34:35]
	v_lshl_add_u64 v[34:35], s[74:75], 0, v[50:51]
	v_lshl_add_u64 v[34:35], v[34:35], 0, v[152:153]
	global_load_dwordx4 v[54:57], v[34:35], off nt
	global_load_dwordx4 v[42:45], v[34:35], off offset:256 nt
	v_add_u32_e32 v34, 0xb0, v154
	v_ashrrev_i32_e32 v35, 31, v34
	v_lshl_add_u64 v[36:37], s[14:15], 0, v[36:37]
	v_lshlrev_b64 v[46:47], 11, v[34:35]
	v_lshl_add_u64 v[52:53], v[36:37], 0, v[152:153]
	v_lshlrev_b64 v[36:37], 12, v[34:35]
	v_lshl_add_u64 v[34:35], s[74:75], 0, v[46:47]
	v_lshl_add_u64 v[36:37], s[14:15], 0, v[36:37]
	v_lshl_add_u64 v[34:35], v[34:35], 0, v[152:153]
	v_lshl_add_u64 v[48:49], v[36:37], 0, v[152:153]
	global_load_dwordx4 v[38:41], v[34:35], off nt
	s_nop 0
	global_load_dwordx4 v[34:37], v[34:35], off offset:256 nt
	s_nop 0
	global_load_dwordx4 v[58:61], v[52:53], off offset:2048 nt
	s_waitcnt vmcnt(4)
	v_cvt_f32_f16_e32 v64, v54
	v_cvt_f32_f16_sdwa v65, v54 dst_sel:DWORD dst_unused:UNUSED_PAD src0_sel:WORD_1
	s_waitcnt vmcnt(0)
	v_cvt_f32_f16_e32 v62, v58
	v_cvt_f32_f16_sdwa v58, v58 dst_sel:DWORD dst_unused:UNUSED_PAD src0_sel:WORD_1
	v_cvt_f32_f16_e32 v54, v59
	v_mul_f32_e32 v62, 0xbfb8aa3b, v62
	v_mul_f32_e32 v58, 0xbfb8aa3b, v58
	v_mul_f32_e32 v54, 0xbfb8aa3b, v54
	v_exp_f32_e32 v58, v58
	v_exp_f32_e32 v54, v54
	v_exp_f32_e32 v62, v62
	v_add_f32_e32 v58, 1.0, v58
	v_add_f32_e32 v54, 1.0, v54
	v_rcp_f32_e32 v63, v58
	v_rcp_f32_e32 v58, v54
	v_cvt_f32_f16_sdwa v54, v59 dst_sel:DWORD dst_unused:UNUSED_PAD src0_sel:WORD_1
	v_add_f32_e32 v62, 1.0, v62
	v_rcp_f32_e32 v62, v62
	v_mul_f32_e32 v54, 0xbfb8aa3b, v54
	v_exp_f32_e32 v54, v54
	v_pk_fma_f32 v[30:31], v[30:31], v[62:63], v[64:65]
	v_add_f32_e32 v54, 1.0, v54
	v_rcp_f32_e32 v59, v54
	v_cvt_f32_f16_e32 v54, v55
	v_cvt_f32_f16_sdwa v55, v55 dst_sel:DWORD dst_unused:UNUSED_PAD src0_sel:WORD_1
	v_cvt_pk_f16_f32 v30, v30, v31
	v_pk_fma_f32 v[32:33], v[32:33], v[58:59], v[54:55]
	v_cvt_f32_f16_e32 v54, v60
	v_cvt_f32_f16_sdwa v55, v60 dst_sel:DWORD dst_unused:UNUSED_PAD src0_sel:WORD_1
	v_cvt_f32_f16_e32 v58, v56
	v_cvt_f32_f16_sdwa v59, v56 dst_sel:DWORD dst_unused:UNUSED_PAD src0_sel:WORD_1
	v_mul_f32_e32 v54, 0xbfb8aa3b, v54
	v_mul_f32_e32 v55, 0xbfb8aa3b, v55
	v_exp_f32_e32 v54, v54
	v_exp_f32_e32 v55, v55
	v_cvt_f32_f16_e32 v56, v57
	v_cvt_f32_f16_sdwa v57, v57 dst_sel:DWORD dst_unused:UNUSED_PAD src0_sel:WORD_1
	v_add_f32_e32 v54, 1.0, v54
	v_add_f32_e32 v55, 1.0, v55
	v_rcp_f32_e32 v54, v54
	v_rcp_f32_e32 v55, v55
	v_cvt_pk_f16_f32 v31, v32, v33
	v_pk_fma_f32 v[26:27], v[26:27], v[54:55], v[58:59]
	v_cvt_f32_f16_e32 v54, v61
	v_cvt_f32_f16_sdwa v55, v61 dst_sel:DWORD dst_unused:UNUSED_PAD src0_sel:WORD_1
	v_cvt_pk_f16_f32 v32, v26, v27
	v_lshl_add_u64 v[26:27], s[24:25], 0, v[50:51]
	v_mul_f32_e32 v54, 0xbfb8aa3b, v54
	v_mul_f32_e32 v55, 0xbfb8aa3b, v55
	v_exp_f32_e32 v54, v54
	v_exp_f32_e32 v55, v55
	v_lshl_add_u64 v[50:51], v[26:27], 0, v[152:153]
	v_add_f32_e32 v54, 1.0, v54
	v_add_f32_e32 v55, 1.0, v55
	v_rcp_f32_e32 v54, v54
	v_rcp_f32_e32 v55, v55
	s_nop 0
	v_pk_fma_f32 v[28:29], v[28:29], v[54:55], v[56:57]
	s_nop 0
	v_cvt_pk_f16_f32 v33, v28, v29
	global_load_dwordx4 v[26:29], v[48:49], off offset:2048 nt
	v_cvt_f32_f16_e32 v54, v42
	global_store_dwordx4 v[50:51], v[30:33], off
	global_load_dwordx4 v[30:33], v[52:53], off offset:2304 nt
	v_cvt_f32_f16_sdwa v55, v42 dst_sel:DWORD dst_unused:UNUSED_PAD src0_sel:WORD_1
	v_cvt_f32_f16_e32 v42, v43
	v_cvt_f32_f16_sdwa v43, v43 dst_sel:DWORD dst_unused:UNUSED_PAD src0_sel:WORD_1
	s_waitcnt vmcnt(0)
; __device__ __forceinline__ unsigned cvtpk(float lo, float hi) { f32x2_t v = {lo, hi}; f16x2_t b = __builtin_convertvector(v, f16x2_t); return __builtin_bit_cast(unsigned, b); }
; __device__ __forceinline__ float bflo(unsigned w) { const f16x2_t b = __builtin_bit_cast(f16x2_t, w); return (float)b[0]; }
; __device__ __forceinline__ float bfhi(unsigned w) { const f16x2_t b = __builtin_bit_cast(f16x2_t, w); return (float)b[1]; }
;     __device__ __forceinline__ void operator()(const f32x4 (&acc)[2][2][4][2], const Unit& u, int wr, int wc, int fr, int fq) const {
;     ...
;                 for (int mm = 0; mm < 2; ++mm)
; #pragma unroll
;                     for (int bj = 0; bj < 2; ++bj) { const int m = 2 * mh + mm; const int row = row0 + ai * HALF + m * 16, col = col0 + bj * HALF; const u32x4 g = gv[mm][bj]; const u32x4 sw = sv[mm][bj]; const f32x4 s0 = (f32x4){bflo(sw.x), bfhi(sw.x), bflo(sw.y), bfhi(sw.y)}, s1 = (f32x4){bflo(sw.z), bfhi(sw.z), bflo(sw.w), bfhi(sw.w)};
;                         f32x4 v0 = acc[ai][bj][m][0], v1 = acc[ai][bj][m][1];
;                         v0[0] = s0[0] + v0[0] * sigmoidf_(bflo(g.x)); v0[1] = s0[1] + v0[1] * sigmoidf_(bfhi(g.x)); v0[2] = s0[2] + v0[2] * sigmoidf_(bflo(g.y)); v0[3] = s0[3] + v0[3] * sigmoidf_(bfhi(g.y));
;                         v1[0] = s1[0] + v1[0] * sigmoidf_(bflo(g.z)); v1[1] = s1[1] + v1[1] * sigmoidf_(bfhi(g.z)); v1[2] = s1[2] + v1[2] * sigmoidf_(bflo(g.w)); v1[3] = s1[3] + v1[3] * sigmoidf_(bfhi(g.w));
;                         u32x4 w; w.x = cvtpk(v0[0], v0[1]); w.y = cvtpk(v0[2], v0[3]); w.z = cvtpk(v1[0], v1[1]); w.w = cvtpk(v1[2], v1[3]);
;                         *(u32x4*)(mrg + (size_t)row * 1024 + col) = w; }
;                 asm volatile("" ::: "memory"); }
; template <class Epi, class Sched, bool ALIGN_EPI = false, bool SP2 = false>
; __device__ __forceinline__ void gemm_phase(PG8_LAS unsigned char* lds, const Gemm g, const Sched& S, const Epi& E) {
;     ...
;         if (!has_next) break;
; #pragma unroll
;         for (int a = 0; a < 2; ++a)
; #pragma unroll
;             for (int b = 0; b < 2; ++b)
; #pragma unroll
;                 for (int m = 0; m < 4; ++m)
; #pragma unroll
;                     for (int n = 0; n < 2; ++n) acc[a][b][m][n] = (f32x4){0.f, 0.f, 0.f, 0.f};
;         cur = nxt; cA = nA; cB = nB; ++ui;
;         if constexpr (ALIGN_EPI) { if (wr == 1) PG8_BAR; }
	v_cvt_f32_f16_e32 v52, v30
	v_cvt_f32_f16_sdwa v30, v30 dst_sel:DWORD dst_unused:UNUSED_PAD src0_sel:WORD_1
	v_mul_f32_e32 v52, 0xbfb8aa3b, v52
	v_mul_f32_e32 v30, 0xbfb8aa3b, v30
	v_exp_f32_e32 v30, v30
	v_exp_f32_e32 v52, v52
	v_add_f32_e32 v30, 1.0, v30
	v_rcp_f32_e32 v53, v30
	v_cvt_f32_f16_e32 v30, v31
	v_cvt_f32_f16_sdwa v31, v31 dst_sel:DWORD dst_unused:UNUSED_PAD src0_sel:WORD_1
	v_add_f32_e32 v52, 1.0, v52
	v_rcp_f32_e32 v52, v52
	v_mul_f32_e32 v30, 0xbfb8aa3b, v30
	v_mul_f32_e32 v31, 0xbfb8aa3b, v31
	v_exp_f32_e32 v30, v30
	v_exp_f32_e32 v31, v31
	v_pk_fma_f32 v[22:23], v[22:23], v[52:53], v[54:55]
	v_add_f32_e32 v30, 1.0, v30
	v_add_f32_e32 v31, 1.0, v31
	v_rcp_f32_e32 v30, v30
	v_rcp_f32_e32 v31, v31
	v_cvt_pk_f16_f32 v22, v22, v23
	v_pk_fma_f32 v[24:25], v[24:25], v[30:31], v[42:43]
	v_cvt_f32_f16_e32 v30, v32
	v_cvt_f32_f16_sdwa v31, v32 dst_sel:DWORD dst_unused:UNUSED_PAD src0_sel:WORD_1
	v_cvt_f32_f16_e32 v42, v44
	v_cvt_f32_f16_sdwa v43, v44 dst_sel:DWORD dst_unused:UNUSED_PAD src0_sel:WORD_1
	v_mul_f32_e32 v30, 0xbfb8aa3b, v30
	v_mul_f32_e32 v31, 0xbfb8aa3b, v31
	v_exp_f32_e32 v30, v30
	v_exp_f32_e32 v31, v31
	v_cvt_f32_f16_e32 v32, v45
	v_cvt_pk_f16_f32 v23, v24, v25
	v_add_f32_e32 v30, 1.0, v30
	v_add_f32_e32 v31, 1.0, v31
	v_rcp_f32_e32 v30, v30
	v_rcp_f32_e32 v31, v31
	s_nop 0
	v_pk_fma_f32 v[18:19], v[18:19], v[30:31], v[42:43]
	v_cvt_f32_f16_e32 v30, v33
	v_cvt_f32_f16_sdwa v31, v33 dst_sel:DWORD dst_unused:UNUSED_PAD src0_sel:WORD_1
	v_cvt_f32_f16_sdwa v33, v45 dst_sel:DWORD dst_unused:UNUSED_PAD src0_sel:WORD_1
	v_cvt_pk_f16_f32 v24, v18, v19
	v_mul_f32_e32 v30, 0xbfb8aa3b, v30
	v_mul_f32_e32 v31, 0xbfb8aa3b, v31
	v_exp_f32_e32 v30, v30
	v_exp_f32_e32 v31, v31
	v_add_f32_e32 v30, 1.0, v30
	v_add_f32_e32 v31, 1.0, v31
	v_rcp_f32_e32 v30, v30
	v_rcp_f32_e32 v31, v31
	s_nop 0
	v_pk_fma_f32 v[20:21], v[20:21], v[30:31], v[32:33]
	s_nop 0
	v_cvt_pk_f16_f32 v25, v20, v21
	global_load_dwordx4 v[18:21], v[48:49], off offset:2304 nt
	s_nop 0
	global_store_dwordx4 v[50:51], v[22:25], off offset:256
	s_nop 1
	v_cvt_f32_f16_e32 v22, v26
	v_cvt_f32_f16_sdwa v23, v26 dst_sel:DWORD dst_unused:UNUSED_PAD src0_sel:WORD_1
	v_cvt_f32_f16_e32 v24, v38
	v_cvt_f32_f16_sdwa v25, v38 dst_sel:DWORD dst_unused:UNUSED_PAD src0_sel:WORD_1
	v_mul_f32_e32 v22, 0xbfb8aa3b, v22
	v_mul_f32_e32 v23, 0xbfb8aa3b, v23
	v_exp_f32_e32 v22, v22
	v_exp_f32_e32 v23, v23
	v_add_f32_e32 v22, 1.0, v22
	v_add_f32_e32 v23, 1.0, v23
	v_rcp_f32_e32 v22, v22
	v_rcp_f32_e32 v23, v23
	s_nop 0
	v_pk_fma_f32 v[14:15], v[14:15], v[22:23], v[24:25]
	v_cvt_f32_f16_e32 v22, v27
	v_cvt_f32_f16_sdwa v23, v27 dst_sel:DWORD dst_unused:UNUSED_PAD src0_sel:WORD_1
	v_cvt_f32_f16_e32 v24, v39
	v_cvt_f32_f16_sdwa v25, v39 dst_sel:DWORD dst_unused:UNUSED_PAD src0_sel:WORD_1
	v_mul_f32_e32 v22, 0xbfb8aa3b, v22
	v_mul_f32_e32 v23, 0xbfb8aa3b, v23
	v_exp_f32_e32 v22, v22
	v_exp_f32_e32 v23, v23
	v_add_f32_e32 v22, 1.0, v22
	v_add_f32_e32 v23, 1.0, v23
	v_rcp_f32_e32 v22, v22
	v_rcp_f32_e32 v23, v23
	s_nop 0
	v_pk_fma_f32 v[16:17], v[16:17], v[22:23], v[24:25]
	v_cvt_f32_f16_e32 v22, v28
	v_cvt_f32_f16_sdwa v23, v28 dst_sel:DWORD dst_unused:UNUSED_PAD src0_sel:WORD_1
	v_cvt_f32_f16_e32 v24, v40
	v_cvt_f32_f16_sdwa v25, v40 dst_sel:DWORD dst_unused:UNUSED_PAD src0_sel:WORD_1
	v_mul_f32_e32 v22, 0xbfb8aa3b, v22
	v_mul_f32_e32 v23, 0xbfb8aa3b, v23
	v_exp_f32_e32 v22, v22
	v_exp_f32_e32 v23, v23
	v_add_f32_e32 v22, 1.0, v22
	v_add_f32_e32 v23, 1.0, v23
	v_rcp_f32_e32 v22, v22
	v_rcp_f32_e32 v23, v23
	s_nop 0
	v_pk_fma_f32 v[10:11], v[10:11], v[22:23], v[24:25]
	v_cvt_f32_f16_e32 v22, v29
	v_cvt_f32_f16_sdwa v23, v29 dst_sel:DWORD dst_unused:UNUSED_PAD src0_sel:WORD_1
	v_cvt_f32_f16_e32 v24, v41
	v_cvt_f32_f16_sdwa v25, v41 dst_sel:DWORD dst_unused:UNUSED_PAD src0_sel:WORD_1
	v_mul_f32_e32 v22, 0xbfb8aa3b, v22
	v_mul_f32_e32 v23, 0xbfb8aa3b, v23
	v_exp_f32_e32 v22, v22
	v_exp_f32_e32 v23, v23
	v_add_f32_e32 v22, 1.0, v22
	v_add_f32_e32 v23, 1.0, v23
	v_rcp_f32_e32 v22, v22
	v_rcp_f32_e32 v23, v23
	s_nop 0
	v_pk_fma_f32 v[22:23], v[12:13], v[22:23], v[24:25]
	v_cvt_pk_f16_f32 v12, v14, v15
	v_cvt_pk_f16_f32 v14, v10, v11
	v_lshl_add_u64 v[10:11], s[24:25], 0, v[46:47]
	v_cvt_pk_f16_f32 v13, v16, v17
	v_cvt_pk_f16_f32 v15, v22, v23
	v_lshl_add_u64 v[10:11], v[10:11], 0, v[152:153]
	global_store_dwordx4 v[10:11], v[12:15], off
	s_mov_b64 s[24:25], -1
	s_waitcnt vmcnt(2)
	v_cvt_f32_f16_e32 v12, v18
	v_cvt_f32_f16_sdwa v13, v18 dst_sel:DWORD dst_unused:UNUSED_PAD src0_sel:WORD_1
	v_cvt_f32_f16_e32 v14, v34
	v_cvt_f32_f16_sdwa v15, v34 dst_sel:DWORD dst_unused:UNUSED_PAD src0_sel:WORD_1
	v_mul_f32_e32 v12, 0xbfb8aa3b, v12
	v_mul_f32_e32 v13, 0xbfb8aa3b, v13
	v_exp_f32_e32 v12, v12
	v_exp_f32_e32 v13, v13
	v_add_f32_e32 v12, 1.0, v12
	v_add_f32_e32 v13, 1.0, v13
	v_rcp_f32_e32 v12, v12
	v_rcp_f32_e32 v13, v13
	s_nop 0
	v_pk_fma_f32 v[6:7], v[6:7], v[12:13], v[14:15]
	v_cvt_f32_f16_e32 v12, v19
	v_cvt_f32_f16_sdwa v13, v19 dst_sel:DWORD dst_unused:UNUSED_PAD src0_sel:WORD_1
	v_cvt_f32_f16_e32 v14, v35
	v_cvt_f32_f16_sdwa v15, v35 dst_sel:DWORD dst_unused:UNUSED_PAD src0_sel:WORD_1
	v_mul_f32_e32 v12, 0xbfb8aa3b, v12
	v_mul_f32_e32 v13, 0xbfb8aa3b, v13
	v_exp_f32_e32 v12, v12
	v_exp_f32_e32 v13, v13
	v_add_f32_e32 v12, 1.0, v12
	v_add_f32_e32 v13, 1.0, v13
	v_rcp_f32_e32 v12, v12
	v_rcp_f32_e32 v13, v13
	s_nop 0
	v_pk_fma_f32 v[8:9], v[8:9], v[12:13], v[14:15]
	v_cvt_f32_f16_e32 v12, v20
	v_cvt_f32_f16_sdwa v13, v20 dst_sel:DWORD dst_unused:UNUSED_PAD src0_sel:WORD_1
	v_cvt_f32_f16_e32 v14, v36
	v_cvt_f32_f16_sdwa v15, v36 dst_sel:DWORD dst_unused:UNUSED_PAD src0_sel:WORD_1
	v_mul_f32_e32 v12, 0xbfb8aa3b, v12
	v_mul_f32_e32 v13, 0xbfb8aa3b, v13
	v_exp_f32_e32 v12, v12
	v_exp_f32_e32 v13, v13
	v_add_f32_e32 v12, 1.0, v12
	v_add_f32_e32 v13, 1.0, v13
	v_rcp_f32_e32 v12, v12
	v_rcp_f32_e32 v13, v13
	s_nop 0
	v_pk_fma_f32 v[12:13], v[2:3], v[12:13], v[14:15]
	v_cvt_f32_f16_e32 v2, v21
	v_cvt_f32_f16_sdwa v3, v21 dst_sel:DWORD dst_unused:UNUSED_PAD src0_sel:WORD_1
	v_cvt_f32_f16_e32 v14, v37
	v_cvt_f32_f16_sdwa v15, v37 dst_sel:DWORD dst_unused:UNUSED_PAD src0_sel:WORD_1
	v_mul_f32_e32 v2, 0xbfb8aa3b, v2
	v_mul_f32_e32 v3, 0xbfb8aa3b, v3
	v_exp_f32_e32 v2, v2
	v_exp_f32_e32 v3, v3
	v_add_f32_e32 v2, 1.0, v2
	v_add_f32_e32 v3, 1.0, v3
	v_rcp_f32_e32 v2, v2
	v_rcp_f32_e32 v3, v3
	s_nop 0
	v_pk_fma_f32 v[14:15], v[4:5], v[2:3], v[14:15]
	v_cvt_pk_f16_f32 v2, v6, v7
	v_cvt_pk_f16_f32 v3, v8, v9
	v_cvt_pk_f16_f32 v4, v12, v13
	v_cvt_pk_f16_f32 v5, v14, v15
	global_store_dwordx4 v[10:11], v[2:5], off offset:256
	s_cbranch_vccnz .LBB0_745
	s_andn2_b64 vcc, exec, s[16:17]
	s_cbranch_vccnz .LBB0_744
	s_barrier
	s_branch .LBB0_744
